# v47 plus stacked attention stage-path trims: stage-head flag re-test skip, exit-only moves off the exp/PV section, fast-tail back-edge rotation
# baseline (speedup 1.0000x reference)
; #define LAS __attribute__((address_space(3)))
; __device__ __forceinline__ unsigned cvtpk2(float lo, float hi) { const f32x2 v = {lo, hi}; const bf16x2_n b = __builtin_convertvector(v, bf16x2_n); return __builtin_bit_cast(unsigned, b); }
; __device__ __forceinline__ void a2_exp_pack(f32x16& st0, f32x16& st1, float& lsum, bf16x8 (&pf)[4]) {
;     float ps = 0.f;
; #pragma unroll
;     for (int r = 0; r < 16; ++r) { st0[r] = __builtin_amdgcn_exp2f(st0[r]); st1[r] = __builtin_amdgcn_exp2f(st1[r]); ps += st0[r] + st1[r]; }
;     lsum += ps;
;     u32x4 w;
;     w.x = cvtpk2(st0[0], st0[1]); w.y = cvtpk2(st0[2], st0[3]); w.z = cvtpk2(st0[4], st0[5]); w.w = cvtpk2(st0[6], st0[7]); pf[0] = __builtin_bit_cast(bf16x8, w);
;     w.x = cvtpk2(st0[8], st0[9]); w.y = cvtpk2(st0[10], st0[11]); w.z = cvtpk2(st0[12], st0[13]); w.w = cvtpk2(st0[14], st0[15]); pf[1] = __builtin_bit_cast(bf16x8, w);
;     w.x = cvtpk2(st1[0], st1[1]); w.y = cvtpk2(st1[2], st1[3]); w.z = cvtpk2(st1[4], st1[5]); w.w = cvtpk2(st1[6], st1[7]); pf[2] = __builtin_bit_cast(bf16x8, w);
;     w.x = cvtpk2(st1[8], st1[9]); w.y = cvtpk2(st1[10], st1[11]); w.z = cvtpk2(st1[12], st1[13]); w.w = cvtpk2(st1[14], st1[15]); pf[3] = __builtin_bit_cast(bf16x8, w);
; }
; __device__ __forceinline__ void a2_pv(const LAS unsigned char* vb, const bf16x8 (&pf)[4], f32x16& ot0, f32x16& ot1) {
; #pragma unroll
;     for (int s = 0; s < 4; ++s) {
;         const s16x4 a00 = __builtin_bit_cast(s16x4, __builtin_amdgcn_ds_read_tr16_b64_v4i16((LAS s16x4*)(vb + (16 * s) * 64)));
;         const s16x4 a01 = __builtin_bit_cast(s16x4, __builtin_amdgcn_ds_read_tr16_b64_v4i16((LAS s16x4*)(vb + (16 * s + 8) * 64)));
;         const s16x4 a10 = __builtin_bit_cast(s16x4, __builtin_amdgcn_ds_read_tr16_b64_v4i16((LAS s16x4*)(vb + 8192 + (16 * s) * 64)));
;         const s16x4 a11 = __builtin_bit_cast(s16x4, __builtin_amdgcn_ds_read_tr16_b64_v4i16((LAS s16x4*)(vb + 8192 + (16 * s + 8) * 64)));
;         const bf16x8 va0 = (bf16x8){a00[0], a00[1], a00[2], a00[3], a01[0], a01[1], a01[2], a01[3]};
;         const bf16x8 va1 = (bf16x8){a10[0], a10[1], a10[2], a10[3], a11[0], a11[1], a11[2], a11[3]};
;         ot0 = __builtin_amdgcn_mfma_f32_32x32x16_bf16(va0, pf[s], ot0, 0, 0, 0); ot1 = __builtin_amdgcn_mfma_f32_32x32x16_bf16(va1, pf[s], ot1, 0, 0, 0); }
; }
.LBB0_832:
	v_add_u32_e32 v0, v2, v218
	v_exp_f32_e32 v199, v112
	v_exp_f32_e32 v7, v96
	v_exp_f32_e32 v113, v113
	v_exp_f32_e32 v9, v97
	v_exp_f32_e32 v201, v114
	v_exp_f32_e32 v3, v98
	v_exp_f32_e32 v115, v115
	v_exp_f32_e32 v5, v99
	v_exp_f32_e32 v203, v116
	v_exp_f32_e32 v15, v117
	v_exp_f32_e32 v13, v118
	v_exp_f32_e32 v11, v119
	s_waitcnt vmcnt(0)
	ds_read_b64_tr_b16 v[96:97], v0 offset:26624
	ds_read_b64_tr_b16 v[98:99], v0 offset:27136
	ds_read_b64_tr_b16 v[214:215], v0 offset:34816
	ds_read_b64_tr_b16 v[216:217], v0 offset:35328
	ds_read_b64_tr_b16 v[224:225], v0 offset:27648
	ds_read_b64_tr_b16 v[226:227], v0 offset:28160
	v_cvt_pk_bf16_f32 v210, v199, v113
	v_cvt_pk_bf16_f32 v211, v201, v115
	v_cvt_pk_bf16_f32 v212, v203, v15
	v_cvt_pk_bf16_f32 v213, v13, v11
	v_exp_f32_e32 v209, v120
	v_exp_f32_e32 v207, v121
	s_waitcnt lgkmcnt(4)
	v_mfma_f32_32x32x16_bf16 v[16:31], v[96:99], v[210:213], v[16:31]
	v_exp_f32_e32 v205, v122
	v_exp_f32_e32 v121, v123
	v_exp_f32_e32 v117, v124
	ds_read_b64_tr_b16 v[228:229], v0 offset:35840
	ds_read_b64_tr_b16 v[230:231], v0 offset:36352
	v_exp_f32_e32 v119, v125
	v_exp_f32_e32 v99, v126
	v_exp_f32_e32 v97, v127
	s_waitcnt lgkmcnt(4)
	v_mfma_f32_32x32x16_bf16 v[32:47], v[214:217], v[210:213], v[32:47]
	v_cvt_pk_bf16_f32 v232, v209, v207
	v_cvt_pk_bf16_f32 v233, v205, v121
	v_cvt_pk_bf16_f32 v234, v117, v119
	v_cvt_pk_bf16_f32 v235, v99, v97
	v_exp_f32_e32 v125, v100
	v_exp_f32_e32 v213, v101
	v_exp_f32_e32 v211, v102
	s_waitcnt lgkmcnt(2)
	v_mfma_f32_32x32x16_bf16 v[16:31], v[224:227], v[232:235], v[16:31]
	v_exp_f32_e32 v217, v103
	ds_read_b64_tr_b16 v[224:225], v0 offset:28672
	ds_read_b64_tr_b16 v[226:227], v0 offset:29184
	v_cvt_pk_bf16_f32 v100, v7, v9
	v_cvt_pk_bf16_f32 v101, v3, v5
	v_cvt_pk_bf16_f32 v102, v125, v213
	v_cvt_pk_bf16_f32 v103, v211, v217
	v_exp_f32_e32 v123, v104
	s_waitcnt lgkmcnt(2)
	v_mfma_f32_32x32x16_bf16 v[32:47], v[228:231], v[232:235], v[32:47]
	ds_read_b64_tr_b16 v[228:229], v0 offset:36864
	ds_read_b64_tr_b16 v[230:231], v0 offset:37376
	ds_read_b64_tr_b16 v[232:233], v0 offset:29696
	ds_read_b64_tr_b16 v[234:235], v0 offset:30208
	v_exp_f32_e32 v127, v105
	v_exp_f32_e32 v105, v106
	v_exp_f32_e32 v215, v107
	v_exp_f32_e32 v107, v108
	v_exp_f32_e32 v109, v109
	v_exp_f32_e32 v198, v64
	s_waitcnt lgkmcnt(4)
	v_mfma_f32_32x32x16_bf16 v[16:31], v[224:227], v[100:103], v[16:31]
	ds_read_b64_tr_b16 v[224:225], v0 offset:37888
	ds_read_b64_tr_b16 v[226:227], v0 offset:38400
	v_exp_f32_e32 v6, v80
	v_exp_f32_e32 v112, v65
	v_exp_f32_e32 v8, v81
	v_exp_f32_e32 v200, v66
	v_exp_f32_e32 v2, v82
	v_exp_f32_e32 v114, v67
	s_waitcnt lgkmcnt(4)
	v_mfma_f32_32x32x16_bf16 v[32:47], v[228:231], v[100:103], v[32:47]
	v_exp_f32_e32 v103, v110
	v_exp_f32_e32 v101, v111
	v_exp_f32_e32 v4, v83
	v_cvt_pk_bf16_f32 v228, v123, v127
	v_cvt_pk_bf16_f32 v229, v105, v215
	v_cvt_pk_bf16_f32 v230, v107, v109
	v_cvt_pk_bf16_f32 v231, v103, v101
	v_pk_add_f32 v[64:65], v[6:7], v[198:199]
	v_pk_add_f32 v[66:67], v[8:9], v[112:113]
	s_waitcnt lgkmcnt(2)
	v_mfma_f32_32x32x16_bf16 v[16:31], v[232:235], v[228:231], v[16:31]
	v_add_f32_e64 v64, v64, 0
	v_add_f32_e64 v65, v65, 0
	v_exp_f32_e32 v202, v68
	v_pk_add_f32 v[64:65], v[66:67], v[64:65]
	v_pk_add_f32 v[66:67], v[2:3], v[200:201]
	v_exp_f32_e32 v14, v69
	v_pk_add_f32 v[64:65], v[66:67], v[64:65]
	v_pk_add_f32 v[66:67], v[4:5], v[114:115]
	s_waitcnt lgkmcnt(0)
	v_mfma_f32_32x32x16_bf16 v[32:47], v[224:227], v[228:231], v[32:47]
	v_add_f32_e64 v110, v66, v64
	v_add_f32_e64 v111, v67, v65
	v_exp_f32_e32 v12, v70
	v_exp_f32_e32 v10, v71
	ds_read_b64_tr_b16 v[64:65], v0 offset:30720
	ds_read_b64_tr_b16 v[66:67], v0 offset:31232
	v_exp_f32_e32 v124, v84
	v_exp_f32_e32 v208, v72
	v_exp_f32_e32 v206, v73
	v_exp_f32_e32 v204, v74
	v_exp_f32_e32 v120, v75
	ds_read_b64_tr_b16 v[72:73], v0 offset:38912
	ds_read_b64_tr_b16 v[74:75], v0 offset:39424
	ds_read_b64_tr_b16 v[80:81], v0 offset:31744
	ds_read_b64_tr_b16 v[82:83], v0 offset:32256
	v_exp_f32_e32 v212, v85
	v_cvt_pk_bf16_f32 v68, v198, v112
	v_cvt_pk_bf16_f32 v69, v200, v114
	v_cvt_pk_bf16_f32 v70, v202, v14
	v_cvt_pk_bf16_f32 v71, v12, v10
	v_pk_add_f32 v[220:221], v[124:125], v[202:203]
	v_exp_f32_e32 v210, v86
	s_waitcnt lgkmcnt(4)
	v_mfma_f32_32x32x16_bf16 v[16:31], v[64:67], v[68:71], v[16:31]
	v_add_f32_e64 v64, v220, v110
	v_add_f32_e64 v65, v221, v111
	v_add_f32_e64 v14, v212, v14
	v_add_f32_e64 v15, v213, v15
	v_exp_f32_e32 v216, v87
	v_exp_f32_e32 v116, v76
	v_exp_f32_e32 v118, v77
	v_exp_f32_e32 v98, v78
	v_exp_f32_e32 v96, v79
	s_waitcnt lgkmcnt(2)
; #define LAS __attribute__((address_space(3)))
; __device__ __forceinline__ void a2_pv(const LAS unsigned char* vb, const bf16x8 (&pf)[4], f32x16& ot0, f32x16& ot1) {
; #pragma unroll
;     for (int s = 0; s < 4; ++s) {
;         const s16x4 a00 = __builtin_bit_cast(s16x4, __builtin_amdgcn_ds_read_tr16_b64_v4i16((LAS s16x4*)(vb + (16 * s) * 64)));
;         const s16x4 a01 = __builtin_bit_cast(s16x4, __builtin_amdgcn_ds_read_tr16_b64_v4i16((LAS s16x4*)(vb + (16 * s + 8) * 64)));
;         const s16x4 a10 = __builtin_bit_cast(s16x4, __builtin_amdgcn_ds_read_tr16_b64_v4i16((LAS s16x4*)(vb + 8192 + (16 * s) * 64)));
;         const s16x4 a11 = __builtin_bit_cast(s16x4, __builtin_amdgcn_ds_read_tr16_b64_v4i16((LAS s16x4*)(vb + 8192 + (16 * s + 8) * 64)));
;         const bf16x8 va0 = (bf16x8){a00[0], a00[1], a00[2], a00[3], a01[0], a01[1], a01[2], a01[3]};
;         const bf16x8 va1 = (bf16x8){a10[0], a10[1], a10[2], a10[3], a11[0], a11[1], a11[2], a11[3]};
;         ot0 = __builtin_amdgcn_mfma_f32_32x32x16_bf16(va0, pf[s], ot0, 0, 0, 0); ot1 = __builtin_amdgcn_mfma_f32_32x32x16_bf16(va1, pf[s], ot1, 0, 0, 0); }
; }
; __device__ __forceinline__ void attn2_unit(bf16_t* Z, const bf16_t* Hb, const float* rc, const float* rs, LAS unsigned char* lds, int b, int h, int qblk) {
;     ...
;             a2_exp_pack(sa0, sa1, lsum, pa);
;             a2_pv(vb, pa, ot0, ot1);
;             a2_exp_pack(sb0, sb1, lsum, pb);
;             a2_pv(vb + 64 * 64, pb, ot0, ot1);
;         } else if (2 * kp <= cw) {
;             f32x16 sa0, sa1; bf16x8 pa[4];
;             a2_qk(kb, qf, cneg, sa0, sa1);
;             const float mt = a2_max(sa0, sa1);
;             if (kp == 0 || __builtin_amdgcn_ballot_w64(mt > 8.f) != 0ull) {
;                 const float delta = (kp == 0) ? mt : fmaxf(mt, 0.f), alpha = (kp == 0) ? 0.f : __builtin_amdgcn_exp2f(-delta);
;                 mrun += delta; lsum *= alpha;
; #pragma unroll
;                 for (int r = 0; r < 16; ++r) { ot0[r] *= alpha; ot1[r] *= alpha; sa0[r] -= delta; sa1[r] -= delta; cneg[r] = -mrun; }
;             }
;             a2_exp_pack(sa0, sa1, lsum, pa);
;             a2_pv(vb, pa, ot0, ot1);
;         }
;         __syncthreads();
;     }
	v_mfma_f32_32x32x16_bf16 v[32:47], v[72:75], v[68:71], v[32:47]
	v_add_f32_e64 v14, v14, v64
	v_add_f32_e64 v15, v15, v65
	ds_read_b64_tr_b16 v[64:65], v0 offset:39936
	ds_read_b64_tr_b16 v[66:67], v0 offset:40448
	v_exp_f32_e32 v122, v88
	v_pk_add_f32 v[12:13], v[210:211], v[12:13]
	v_pk_add_f32 v[68:69], v[216:217], v[10:11]
	v_pk_add_f32 v[14:15], v[12:13], v[14:15]
	v_cvt_pk_bf16_f32 v10, v208, v206
	v_cvt_pk_bf16_f32 v11, v204, v120
	v_cvt_pk_bf16_f32 v12, v116, v118
	v_cvt_pk_bf16_f32 v13, v98, v96
	v_pk_add_f32 v[14:15], v[68:69], v[14:15]
	v_pk_add_f32 v[68:69], v[122:123], v[208:209]
	s_waitcnt lgkmcnt(2)
	v_mfma_f32_32x32x16_bf16 v[16:31], v[80:83], v[10:13], v[16:31]
	v_add_f32_e64 v14, v68, v14
	v_add_f32_e64 v15, v69, v15
	ds_read_b64_tr_b16 v[68:69], v0 offset:32768
	ds_read_b64_tr_b16 v[70:71], v0 offset:33280
	v_exp_f32_e32 v126, v89
	v_exp_f32_e32 v104, v90
	v_cvt_pk_bf16_f32 v7, v2, v4
	v_exp_f32_e32 v214, v91
	v_cvt_pk_bf16_f32 v6, v6, v8
	s_waitcnt lgkmcnt(2)
	v_mfma_f32_32x32x16_bf16 v[32:47], v[64:67], v[10:13], v[32:47]
	ds_read_b64_tr_b16 v[2:3], v0 offset:40960
	ds_read_b64_tr_b16 v[4:5], v0 offset:41472
	ds_read_b64_tr_b16 v[10:11], v0 offset:33792
	ds_read_b64_tr_b16 v[12:13], v0 offset:34304
	v_cvt_pk_bf16_f32 v8, v124, v212
	v_cvt_pk_bf16_f32 v9, v210, v216
	v_pk_add_f32 v[72:73], v[126:127], v[206:207]
	v_pk_add_f32 v[64:65], v[104:105], v[204:205]
	v_pk_add_f32 v[14:15], v[72:73], v[14:15]
	v_exp_f32_e32 v106, v92
	s_waitcnt lgkmcnt(4)
	v_mfma_f32_32x32x16_bf16 v[16:31], v[68:71], v[6:9], v[16:31]
	v_add_f32_e64 v14, v64, v14
	v_add_f32_e64 v15, v65, v15
	v_add_f32_e64 v64, v214, v120
	v_add_f32_e64 v65, v215, v121
	v_exp_f32_e32 v108, v93
	v_exp_f32_e32 v102, v94
	v_exp_f32_e32 v100, v95
	v_pk_add_f32 v[14:15], v[64:65], v[14:15]
	ds_read_b64_tr_b16 v[64:65], v0 offset:41984
	ds_read_b64_tr_b16 v[66:67], v0 offset:42496
	s_waitcnt lgkmcnt(4)
	v_mfma_f32_32x32x16_bf16 v[32:47], v[2:5], v[6:9], v[32:47]
	v_add_f32_e64 v2, v106, v116
	v_add_f32_e64 v3, v107, v117
	v_cvt_pk_bf16_f32 v4, v106, v108
	v_add_f32_e64 v6, v2, v14
	v_add_f32_e64 v7, v3, v15
	v_cvt_pk_bf16_f32 v2, v122, v126
	v_cvt_pk_bf16_f32 v3, v104, v214
	v_cvt_pk_bf16_f32 v5, v102, v100
	v_pk_add_f32 v[8:9], v[108:109], v[118:119]
	s_waitcnt lgkmcnt(2)
	v_mfma_f32_32x32x16_bf16 v[16:31], v[10:13], v[2:5], v[16:31]
	v_add_f32_e64 v6, v8, v6
	v_add_f32_e64 v7, v9, v7
	v_add_f32_e64 v8, v102, v98
	v_add_f32_e64 v9, v103, v99
	v_pk_add_f32 v[6:7], v[8:9], v[6:7]
	v_pk_add_f32 v[8:9], v[100:101], v[96:97]
	v_pk_add_f32 v[6:7], v[8:9], v[6:7]
	s_waitcnt lgkmcnt(0)
	v_mfma_f32_32x32x16_bf16 v[32:47], v[64:67], v[2:5], v[32:47]
	v_add_f32_e32 v0, v169, v7
	v_add_f32_e32 v0, v6, v0
	s_add_i32 s65, s65, 1
	s_add_i32 s69, s69, 2
	s_add_i32 s6, s43, s65
	v_lshl_add_u64 v[176:177], v[176:177], 0, v[174:175]
	v_lshl_add_u64 v[178:179], v[178:179], 0, s[20:21]
	v_lshl_add_u64 v[180:181], v[180:181], 0, s[20:21]
	v_lshl_add_u64 v[184:185], v[184:185], 0, v[182:183]
	v_lshl_add_u64 v[188:189], v[188:189], 0, v[186:187]
	s_cmp_lg_u32 s6, 1
	v_lshl_add_u64 v[196:197], v[196:197], 0, v[190:191]
	s_cbranch_scc0 .Lattn_exit_0
	v_mov_b32_e32 v169, v0
	s_bitcmp1_b32 s65, 0
	s_cselect_b32 s6, 0, 0xa800
	s_cmp_ge_u32 s65, s36
	s_waitcnt vmcnt(0) lgkmcnt(0)
	s_barrier
	s_cbranch_scc0 .LBB0_810
	s_branch .LBB0_813
.Lattn_exit_0:
	s_waitcnt vmcnt(0) lgkmcnt(0)
	s_barrier
	s_nop 7
	s_nop 7
	v_mov_b32_e32 v14, v55
	v_mov_b32_e32 v10, v59
	v_mov_b32_e32 v11, v58
	v_mov_b64_e32 v[110:111], v[30:31]
	v_mov_b32_e32 v6, v63
	v_mov_b32_e32 v7, v62
	v_mov_b32_e32 v8, v61
	v_mov_b32_e32 v9, v60
	v_mov_b64_e32 v[126:127], v[46:47]
	v_mov_b32_e32 v12, v57
	v_mov_b32_e32 v13, v56
	v_mov_b32_e32 v15, v54
	v_mov_b32_e32 v171, v53
	v_mov_b32_e32 v198, v52
	v_mov_b32_e32 v199, v51
	v_mov_b32_e32 v200, v50
	v_mov_b32_e32 v201, v49
	v_mov_b32_e32 v4, v48
	v_mov_b32_e32 v5, v165
	v_mov_b64_e32 v[108:109], v[28:29]
	v_mov_b64_e32 v[106:107], v[26:27]
	v_mov_b64_e32 v[104:105], v[24:25]
	v_mov_b64_e32 v[102:103], v[22:23]
	v_mov_b64_e32 v[100:101], v[20:21]
	v_mov_b64_e32 v[98:99], v[18:19]
	v_mov_b64_e32 v[96:97], v[16:17]
	v_mov_b64_e32 v[124:125], v[44:45]
	v_mov_b64_e32 v[122:123], v[42:43]
	v_mov_b64_e32 v[120:121], v[40:41]
	v_mov_b64_e32 v[118:119], v[38:39]
	v_mov_b64_e32 v[116:117], v[36:37]
	v_mov_b64_e32 v[114:115], v[34:35]
	v_mov_b64_e32 v[112:113], v[32:33]
	s_branch .LBB0_837

; #define LAS __attribute__((address_space(3)))
; __device__ __forceinline__ unsigned cvtpk2(float lo, float hi) { const f32x2 v = {lo, hi}; const bf16x2_n b = __builtin_convertvector(v, bf16x2_n); return __builtin_bit_cast(unsigned, b); }
; __device__ __forceinline__ void a2_exp_pack(f32x16& st0, f32x16& st1, float& lsum, bf16x8 (&pf)[4]) {
;     float ps = 0.f;
; #pragma unroll
;     for (int r = 0; r < 16; ++r) { st0[r] = __builtin_amdgcn_exp2f(st0[r]); st1[r] = __builtin_amdgcn_exp2f(st1[r]); ps += st0[r] + st1[r]; }
;     lsum += ps;
;     u32x4 w;
;     w.x = cvtpk2(st0[0], st0[1]); w.y = cvtpk2(st0[2], st0[3]); w.z = cvtpk2(st0[4], st0[5]); w.w = cvtpk2(st0[6], st0[7]); pf[0] = __builtin_bit_cast(bf16x8, w);
;     w.x = cvtpk2(st0[8], st0[9]); w.y = cvtpk2(st0[10], st0[11]); w.z = cvtpk2(st0[12], st0[13]); w.w = cvtpk2(st0[14], st0[15]); pf[1] = __builtin_bit_cast(bf16x8, w);
;     w.x = cvtpk2(st1[0], st1[1]); w.y = cvtpk2(st1[2], st1[3]); w.z = cvtpk2(st1[4], st1[5]); w.w = cvtpk2(st1[6], st1[7]); pf[2] = __builtin_bit_cast(bf16x8, w);
;     w.x = cvtpk2(st1[8], st1[9]); w.y = cvtpk2(st1[10], st1[11]); w.z = cvtpk2(st1[12], st1[13]); w.w = cvtpk2(st1[14], st1[15]); pf[3] = __builtin_bit_cast(bf16x8, w);
; }
; __device__ __forceinline__ void a2_pv(const LAS unsigned char* vb, const bf16x8 (&pf)[4], f32x16& ot0, f32x16& ot1) {
; #pragma unroll
;     for (int s = 0; s < 4; ++s) {
;         const s16x4 a00 = __builtin_bit_cast(s16x4, __builtin_amdgcn_ds_read_tr16_b64_v4i16((LAS s16x4*)(vb + (16 * s) * 64)));
;         const s16x4 a01 = __builtin_bit_cast(s16x4, __builtin_amdgcn_ds_read_tr16_b64_v4i16((LAS s16x4*)(vb + (16 * s + 8) * 64)));
;         const s16x4 a10 = __builtin_bit_cast(s16x4, __builtin_amdgcn_ds_read_tr16_b64_v4i16((LAS s16x4*)(vb + 8192 + (16 * s) * 64)));
;         const s16x4 a11 = __builtin_bit_cast(s16x4, __builtin_amdgcn_ds_read_tr16_b64_v4i16((LAS s16x4*)(vb + 8192 + (16 * s + 8) * 64)));
;         const bf16x8 va0 = (bf16x8){a00[0], a00[1], a00[2], a00[3], a01[0], a01[1], a01[2], a01[3]};
;         const bf16x8 va1 = (bf16x8){a10[0], a10[1], a10[2], a10[3], a11[0], a11[1], a11[2], a11[3]};
;         ot0 = __builtin_amdgcn_mfma_f32_32x32x16_bf16(va0, pf[s], ot0, 0, 0, 0); ot1 = __builtin_amdgcn_mfma_f32_32x32x16_bf16(va1, pf[s], ot1, 0, 0, 0); }
; }
.LBB0_878:
	v_add_u32_e32 v0, v2, v218
	v_exp_f32_e32 v197, v112
	v_exp_f32_e32 v7, v96
	v_exp_f32_e32 v113, v113
	v_exp_f32_e32 v9, v97
	v_exp_f32_e32 v199, v114
	v_exp_f32_e32 v3, v98
	v_exp_f32_e32 v115, v115
	v_exp_f32_e32 v5, v99
	v_exp_f32_e32 v201, v116
	v_exp_f32_e32 v15, v117
	v_exp_f32_e32 v13, v118
	v_exp_f32_e32 v11, v119
	s_waitcnt vmcnt(0)
	ds_read_b64_tr_b16 v[96:97], v0 offset:26624
	ds_read_b64_tr_b16 v[98:99], v0 offset:27136
	ds_read_b64_tr_b16 v[212:213], v0 offset:34816
	ds_read_b64_tr_b16 v[214:215], v0 offset:35328
	ds_read_b64_tr_b16 v[224:225], v0 offset:27648
	ds_read_b64_tr_b16 v[226:227], v0 offset:28160
	v_cvt_pk_bf16_f32 v208, v197, v113
	v_cvt_pk_bf16_f32 v209, v199, v115
	v_cvt_pk_bf16_f32 v210, v201, v15
	v_cvt_pk_bf16_f32 v211, v13, v11
	v_exp_f32_e32 v207, v120
	v_exp_f32_e32 v205, v121
	s_waitcnt lgkmcnt(4)
	v_mfma_f32_32x32x16_bf16 v[16:31], v[96:99], v[208:211], v[16:31]
	v_exp_f32_e32 v203, v122
	v_exp_f32_e32 v121, v123
	v_exp_f32_e32 v117, v124
	ds_read_b64_tr_b16 v[228:229], v0 offset:35840
	ds_read_b64_tr_b16 v[230:231], v0 offset:36352
	v_exp_f32_e32 v119, v125
	v_exp_f32_e32 v99, v126
	v_exp_f32_e32 v97, v127
	s_waitcnt lgkmcnt(4)
	v_mfma_f32_32x32x16_bf16 v[32:47], v[212:215], v[208:211], v[32:47]
	v_cvt_pk_bf16_f32 v232, v207, v205
	v_cvt_pk_bf16_f32 v233, v203, v121
	v_cvt_pk_bf16_f32 v234, v117, v119
	v_cvt_pk_bf16_f32 v235, v99, v97
	v_exp_f32_e32 v125, v100
	v_exp_f32_e32 v211, v101
	v_exp_f32_e32 v209, v102
	s_waitcnt lgkmcnt(2)
	v_mfma_f32_32x32x16_bf16 v[16:31], v[224:227], v[232:235], v[16:31]
	v_exp_f32_e32 v215, v103
	ds_read_b64_tr_b16 v[224:225], v0 offset:28672
	ds_read_b64_tr_b16 v[226:227], v0 offset:29184
	v_cvt_pk_bf16_f32 v100, v7, v9
	v_cvt_pk_bf16_f32 v101, v3, v5
	v_cvt_pk_bf16_f32 v102, v125, v211
	v_cvt_pk_bf16_f32 v103, v209, v215
	v_exp_f32_e32 v123, v104
	s_waitcnt lgkmcnt(2)
	v_mfma_f32_32x32x16_bf16 v[32:47], v[228:231], v[232:235], v[32:47]
	ds_read_b64_tr_b16 v[228:229], v0 offset:36864
	ds_read_b64_tr_b16 v[230:231], v0 offset:37376
	ds_read_b64_tr_b16 v[232:233], v0 offset:29696
	ds_read_b64_tr_b16 v[234:235], v0 offset:30208
	v_exp_f32_e32 v127, v105
	v_exp_f32_e32 v105, v106
	v_exp_f32_e32 v213, v107
	v_exp_f32_e32 v107, v108
	v_exp_f32_e32 v109, v109
	v_exp_f32_e32 v196, v64
	s_waitcnt lgkmcnt(4)
	v_mfma_f32_32x32x16_bf16 v[16:31], v[224:227], v[100:103], v[16:31]
	ds_read_b64_tr_b16 v[224:225], v0 offset:37888
	ds_read_b64_tr_b16 v[226:227], v0 offset:38400
	v_exp_f32_e32 v6, v80
	v_exp_f32_e32 v112, v65
	v_exp_f32_e32 v8, v81
	v_exp_f32_e32 v198, v66
	v_exp_f32_e32 v2, v82
	v_exp_f32_e32 v114, v67
	s_waitcnt lgkmcnt(4)
	v_mfma_f32_32x32x16_bf16 v[32:47], v[228:231], v[100:103], v[32:47]
	v_exp_f32_e32 v103, v110
	v_exp_f32_e32 v101, v111
	v_exp_f32_e32 v4, v83
	v_cvt_pk_bf16_f32 v228, v123, v127
	v_cvt_pk_bf16_f32 v229, v105, v213
	v_cvt_pk_bf16_f32 v230, v107, v109
	v_cvt_pk_bf16_f32 v231, v103, v101
	v_pk_add_f32 v[64:65], v[6:7], v[196:197]
	v_pk_add_f32 v[66:67], v[8:9], v[112:113]
	s_waitcnt lgkmcnt(2)
	v_mfma_f32_32x32x16_bf16 v[16:31], v[232:235], v[228:231], v[16:31]
	v_add_f32_e64 v64, v64, 0
	v_add_f32_e64 v65, v65, 0
	v_exp_f32_e32 v200, v68
	v_pk_add_f32 v[64:65], v[66:67], v[64:65]
	v_pk_add_f32 v[66:67], v[2:3], v[198:199]
	v_exp_f32_e32 v14, v69
	v_pk_add_f32 v[64:65], v[66:67], v[64:65]
	v_pk_add_f32 v[66:67], v[4:5], v[114:115]
	s_waitcnt lgkmcnt(0)
	v_mfma_f32_32x32x16_bf16 v[32:47], v[224:227], v[228:231], v[32:47]
	v_add_f32_e64 v110, v66, v64
	v_add_f32_e64 v111, v67, v65
	v_exp_f32_e32 v12, v70
	v_exp_f32_e32 v10, v71
	ds_read_b64_tr_b16 v[64:65], v0 offset:30720
	ds_read_b64_tr_b16 v[66:67], v0 offset:31232
	v_exp_f32_e32 v124, v84
	v_exp_f32_e32 v206, v72
	v_exp_f32_e32 v204, v73
	v_exp_f32_e32 v202, v74
	v_exp_f32_e32 v120, v75
	ds_read_b64_tr_b16 v[72:73], v0 offset:38912
	ds_read_b64_tr_b16 v[74:75], v0 offset:39424
	ds_read_b64_tr_b16 v[80:81], v0 offset:31744
	ds_read_b64_tr_b16 v[82:83], v0 offset:32256
	v_exp_f32_e32 v210, v85
	v_cvt_pk_bf16_f32 v68, v196, v112
	v_cvt_pk_bf16_f32 v69, v198, v114
	v_cvt_pk_bf16_f32 v70, v200, v14
	v_cvt_pk_bf16_f32 v71, v12, v10
	v_pk_add_f32 v[216:217], v[124:125], v[200:201]
	v_exp_f32_e32 v208, v86
	s_waitcnt lgkmcnt(4)
	v_mfma_f32_32x32x16_bf16 v[16:31], v[64:67], v[68:71], v[16:31]
	v_add_f32_e64 v64, v216, v110
	v_add_f32_e64 v65, v217, v111
	v_add_f32_e64 v14, v210, v14
	v_add_f32_e64 v15, v211, v15
	v_exp_f32_e32 v214, v87
	v_exp_f32_e32 v116, v76
	v_exp_f32_e32 v118, v77
	v_exp_f32_e32 v98, v78
	v_exp_f32_e32 v96, v79
	s_waitcnt lgkmcnt(2)
; #define LAS __attribute__((address_space(3)))
; __device__ __forceinline__ void a2_pv(const LAS unsigned char* vb, const bf16x8 (&pf)[4], f32x16& ot0, f32x16& ot1) {
; #pragma unroll
;     for (int s = 0; s < 4; ++s) {
;         const s16x4 a00 = __builtin_bit_cast(s16x4, __builtin_amdgcn_ds_read_tr16_b64_v4i16((LAS s16x4*)(vb + (16 * s) * 64)));
;         const s16x4 a01 = __builtin_bit_cast(s16x4, __builtin_amdgcn_ds_read_tr16_b64_v4i16((LAS s16x4*)(vb + (16 * s + 8) * 64)));
;         const s16x4 a10 = __builtin_bit_cast(s16x4, __builtin_amdgcn_ds_read_tr16_b64_v4i16((LAS s16x4*)(vb + 8192 + (16 * s) * 64)));
;         const s16x4 a11 = __builtin_bit_cast(s16x4, __builtin_amdgcn_ds_read_tr16_b64_v4i16((LAS s16x4*)(vb + 8192 + (16 * s + 8) * 64)));
;         const bf16x8 va0 = (bf16x8){a00[0], a00[1], a00[2], a00[3], a01[0], a01[1], a01[2], a01[3]};
;         const bf16x8 va1 = (bf16x8){a10[0], a10[1], a10[2], a10[3], a11[0], a11[1], a11[2], a11[3]};
;         ot0 = __builtin_amdgcn_mfma_f32_32x32x16_bf16(va0, pf[s], ot0, 0, 0, 0); ot1 = __builtin_amdgcn_mfma_f32_32x32x16_bf16(va1, pf[s], ot1, 0, 0, 0); }
; }
; __device__ __forceinline__ void attn2_unit(bf16_t* Z, const bf16_t* Hb, const float* rc, const float* rs, LAS unsigned char* lds, int b, int h, int qblk) {
;     ...
;             a2_exp_pack(sa0, sa1, lsum, pa);
;             a2_pv(vb, pa, ot0, ot1);
;             a2_exp_pack(sb0, sb1, lsum, pb);
;             a2_pv(vb + 64 * 64, pb, ot0, ot1);
;         } else if (2 * kp <= cw) {
;             f32x16 sa0, sa1; bf16x8 pa[4];
;             a2_qk(kb, qf, cneg, sa0, sa1);
;             const float mt = a2_max(sa0, sa1);
;             if (kp == 0 || __builtin_amdgcn_ballot_w64(mt > 8.f) != 0ull) {
;                 const float delta = (kp == 0) ? mt : fmaxf(mt, 0.f), alpha = (kp == 0) ? 0.f : __builtin_amdgcn_exp2f(-delta);
;                 mrun += delta; lsum *= alpha;
; #pragma unroll
;                 for (int r = 0; r < 16; ++r) { ot0[r] *= alpha; ot1[r] *= alpha; sa0[r] -= delta; sa1[r] -= delta; cneg[r] = -mrun; }
;             }
;             a2_exp_pack(sa0, sa1, lsum, pa);
;             a2_pv(vb, pa, ot0, ot1);
;         }
;         __syncthreads();
;     }
	v_mfma_f32_32x32x16_bf16 v[32:47], v[72:75], v[68:71], v[32:47]
	v_add_f32_e64 v14, v14, v64
	v_add_f32_e64 v15, v15, v65
	ds_read_b64_tr_b16 v[64:65], v0 offset:39936
	ds_read_b64_tr_b16 v[66:67], v0 offset:40448
	v_exp_f32_e32 v122, v88
	v_pk_add_f32 v[12:13], v[208:209], v[12:13]
	v_pk_add_f32 v[68:69], v[214:215], v[10:11]
	v_pk_add_f32 v[14:15], v[12:13], v[14:15]
	v_cvt_pk_bf16_f32 v10, v206, v204
	v_cvt_pk_bf16_f32 v11, v202, v120
	v_cvt_pk_bf16_f32 v12, v116, v118
	v_cvt_pk_bf16_f32 v13, v98, v96
	v_pk_add_f32 v[14:15], v[68:69], v[14:15]
	v_pk_add_f32 v[68:69], v[122:123], v[206:207]
	s_waitcnt lgkmcnt(2)
	v_mfma_f32_32x32x16_bf16 v[16:31], v[80:83], v[10:13], v[16:31]
	v_add_f32_e64 v14, v68, v14
	v_add_f32_e64 v15, v69, v15
	ds_read_b64_tr_b16 v[68:69], v0 offset:32768
	ds_read_b64_tr_b16 v[70:71], v0 offset:33280
	v_exp_f32_e32 v126, v89
	v_exp_f32_e32 v104, v90
	v_cvt_pk_bf16_f32 v7, v2, v4
	v_exp_f32_e32 v212, v91
	v_cvt_pk_bf16_f32 v6, v6, v8
	s_waitcnt lgkmcnt(2)
	v_mfma_f32_32x32x16_bf16 v[32:47], v[64:67], v[10:13], v[32:47]
	ds_read_b64_tr_b16 v[2:3], v0 offset:40960
	ds_read_b64_tr_b16 v[4:5], v0 offset:41472
	ds_read_b64_tr_b16 v[10:11], v0 offset:33792
	ds_read_b64_tr_b16 v[12:13], v0 offset:34304
	v_cvt_pk_bf16_f32 v8, v124, v210
	v_cvt_pk_bf16_f32 v9, v208, v214
	v_pk_add_f32 v[72:73], v[126:127], v[204:205]
	v_pk_add_f32 v[64:65], v[104:105], v[202:203]
	v_pk_add_f32 v[14:15], v[72:73], v[14:15]
	v_exp_f32_e32 v106, v92
	s_waitcnt lgkmcnt(4)
	v_mfma_f32_32x32x16_bf16 v[16:31], v[68:71], v[6:9], v[16:31]
	v_add_f32_e64 v14, v64, v14
	v_add_f32_e64 v15, v65, v15
	v_add_f32_e64 v64, v212, v120
	v_add_f32_e64 v65, v213, v121
	v_exp_f32_e32 v108, v93
	v_exp_f32_e32 v102, v94
	v_exp_f32_e32 v100, v95
	v_pk_add_f32 v[14:15], v[64:65], v[14:15]
	ds_read_b64_tr_b16 v[64:65], v0 offset:41984
	ds_read_b64_tr_b16 v[66:67], v0 offset:42496
	s_waitcnt lgkmcnt(4)
	v_mfma_f32_32x32x16_bf16 v[32:47], v[2:5], v[6:9], v[32:47]
	v_add_f32_e64 v2, v106, v116
	v_add_f32_e64 v3, v107, v117
	v_cvt_pk_bf16_f32 v4, v106, v108
	v_add_f32_e64 v6, v2, v14
	v_add_f32_e64 v7, v3, v15
	v_cvt_pk_bf16_f32 v2, v122, v126
	v_cvt_pk_bf16_f32 v3, v104, v212
	v_cvt_pk_bf16_f32 v5, v102, v100
	v_pk_add_f32 v[8:9], v[108:109], v[118:119]
	s_waitcnt lgkmcnt(2)
	v_mfma_f32_32x32x16_bf16 v[16:31], v[10:13], v[2:5], v[16:31]
	v_add_f32_e64 v6, v8, v6
	v_add_f32_e64 v7, v9, v7
	v_add_f32_e64 v8, v102, v98
	v_add_f32_e64 v9, v103, v99
	v_pk_add_f32 v[6:7], v[8:9], v[6:7]
	v_pk_add_f32 v[8:9], v[100:101], v[96:97]
	v_pk_add_f32 v[6:7], v[8:9], v[6:7]
	s_waitcnt lgkmcnt(0)
	v_mfma_f32_32x32x16_bf16 v[32:47], v[64:67], v[2:5], v[32:47]
	v_add_f32_e32 v0, v169, v7
	v_add_f32_e32 v0, v6, v0
	s_add_i32 s35, s35, 1
	s_add_i32 s56, s56, 2
	s_add_i32 s6, s46, s35
	v_lshl_add_u64 v[174:175], v[174:175], 0, v[170:171]
	v_lshl_add_u64 v[176:177], v[176:177], 0, s[20:21]
	v_lshl_add_u64 v[178:179], v[178:179], 0, s[20:21]
	v_lshl_add_u64 v[182:183], v[182:183], 0, v[180:181]
	v_lshl_add_u64 v[186:187], v[186:187], 0, v[184:185]
	s_cmp_lg_u32 s6, 1
	v_lshl_add_u64 v[190:191], v[190:191], 0, v[188:189]
	s_cbranch_scc0 .Lattn_exit_1
	v_mov_b32_e32 v169, v0
	s_bitcmp1_b32 s35, 0
	s_cselect_b32 s6, 0, 0xa800
	s_cmp_ge_u32 s35, s42
	s_waitcnt vmcnt(0) lgkmcnt(0)
	s_barrier
	s_cbranch_scc0 .LBB0_856
	s_branch .LBB0_859
.Lattn_exit_1:
	s_waitcnt vmcnt(0) lgkmcnt(0)
	s_barrier
	s_nop 7
	s_nop 7
	v_mov_b32_e32 v14, v55
	v_mov_b32_e32 v10, v59
	v_mov_b32_e32 v11, v58
	v_mov_b64_e32 v[110:111], v[30:31]
	v_mov_b32_e32 v6, v63
	v_mov_b32_e32 v7, v62
	v_mov_b32_e32 v8, v61
	v_mov_b32_e32 v9, v60
	v_mov_b64_e32 v[126:127], v[46:47]
	v_mov_b32_e32 v12, v57
	v_mov_b32_e32 v13, v56
	v_mov_b32_e32 v15, v54
	v_mov_b32_e32 v196, v53
	v_mov_b32_e32 v197, v52
	v_mov_b32_e32 v198, v51
	v_mov_b32_e32 v199, v50
	v_mov_b32_e32 v200, v49
	v_mov_b32_e32 v4, v48
	v_mov_b32_e32 v5, v165
	v_mov_b64_e32 v[108:109], v[28:29]
	v_mov_b64_e32 v[106:107], v[26:27]
	v_mov_b64_e32 v[104:105], v[24:25]
	v_mov_b64_e32 v[102:103], v[22:23]
	v_mov_b64_e32 v[100:101], v[20:21]
	v_mov_b64_e32 v[98:99], v[18:19]
	v_mov_b64_e32 v[96:97], v[16:17]
	v_mov_b64_e32 v[124:125], v[44:45]
	v_mov_b64_e32 v[122:123], v[42:43]
	v_mov_b64_e32 v[120:121], v[40:41]
	v_mov_b64_e32 v[118:119], v[38:39]
	v_mov_b64_e32 v[116:117], v[36:37]
	v_mov_b64_e32 v[114:115], v[34:35]
	v_mov_b64_e32 v[112:113], v[32:33]
	s_branch .LBB0_790

; #define LAS __attribute__((address_space(3)))
; __device__ __forceinline__ unsigned cvtpk2(float lo, float hi) { const f32x2 v = {lo, hi}; const bf16x2_n b = __builtin_convertvector(v, bf16x2_n); return __builtin_bit_cast(unsigned, b); }
; __device__ __forceinline__ void a2_exp_pack(f32x16& st0, f32x16& st1, float& lsum, bf16x8 (&pf)[4]) {
;     float ps = 0.f;
; #pragma unroll
;     for (int r = 0; r < 16; ++r) { st0[r] = __builtin_amdgcn_exp2f(st0[r]); st1[r] = __builtin_amdgcn_exp2f(st1[r]); ps += st0[r] + st1[r]; }
;     lsum += ps;
;     u32x4 w;
;     w.x = cvtpk2(st0[0], st0[1]); w.y = cvtpk2(st0[2], st0[3]); w.z = cvtpk2(st0[4], st0[5]); w.w = cvtpk2(st0[6], st0[7]); pf[0] = __builtin_bit_cast(bf16x8, w);
;     w.x = cvtpk2(st0[8], st0[9]); w.y = cvtpk2(st0[10], st0[11]); w.z = cvtpk2(st0[12], st0[13]); w.w = cvtpk2(st0[14], st0[15]); pf[1] = __builtin_bit_cast(bf16x8, w);
;     w.x = cvtpk2(st1[0], st1[1]); w.y = cvtpk2(st1[2], st1[3]); w.z = cvtpk2(st1[4], st1[5]); w.w = cvtpk2(st1[6], st1[7]); pf[2] = __builtin_bit_cast(bf16x8, w);
;     w.x = cvtpk2(st1[8], st1[9]); w.y = cvtpk2(st1[10], st1[11]); w.z = cvtpk2(st1[12], st1[13]); w.w = cvtpk2(st1[14], st1[15]); pf[3] = __builtin_bit_cast(bf16x8, w);
; }
; __device__ __forceinline__ void a2_pv(const LAS unsigned char* vb, const bf16x8 (&pf)[4], f32x16& ot0, f32x16& ot1) {
; #pragma unroll
;     for (int s = 0; s < 4; ++s) {
;         const s16x4 a00 = __builtin_bit_cast(s16x4, __builtin_amdgcn_ds_read_tr16_b64_v4i16((LAS s16x4*)(vb + (16 * s) * 64)));
;         const s16x4 a01 = __builtin_bit_cast(s16x4, __builtin_amdgcn_ds_read_tr16_b64_v4i16((LAS s16x4*)(vb + (16 * s + 8) * 64)));
;         const s16x4 a10 = __builtin_bit_cast(s16x4, __builtin_amdgcn_ds_read_tr16_b64_v4i16((LAS s16x4*)(vb + 8192 + (16 * s) * 64)));
;         const s16x4 a11 = __builtin_bit_cast(s16x4, __builtin_amdgcn_ds_read_tr16_b64_v4i16((LAS s16x4*)(vb + 8192 + (16 * s + 8) * 64)));
;         const bf16x8 va0 = (bf16x8){a00[0], a00[1], a00[2], a00[3], a01[0], a01[1], a01[2], a01[3]};
;         const bf16x8 va1 = (bf16x8){a10[0], a10[1], a10[2], a10[3], a11[0], a11[1], a11[2], a11[3]};
;         ot0 = __builtin_amdgcn_mfma_f32_32x32x16_bf16(va0, pf[s], ot0, 0, 0, 0); ot1 = __builtin_amdgcn_mfma_f32_32x32x16_bf16(va1, pf[s], ot1, 0, 0, 0); }
; }
.LBB0_2243:
	v_add_u32_e32 v0, v2, v218
	v_exp_f32_e32 v199, v112
	v_exp_f32_e32 v7, v96
	v_exp_f32_e32 v113, v113
	v_exp_f32_e32 v9, v97
	v_exp_f32_e32 v201, v114
	v_exp_f32_e32 v3, v98
	v_exp_f32_e32 v115, v115
	v_exp_f32_e32 v5, v99
	v_exp_f32_e32 v203, v116
	v_exp_f32_e32 v15, v117
	v_exp_f32_e32 v13, v118
	v_exp_f32_e32 v11, v119
	s_waitcnt vmcnt(0)
	ds_read_b64_tr_b16 v[96:97], v0 offset:26624
	ds_read_b64_tr_b16 v[98:99], v0 offset:27136
	ds_read_b64_tr_b16 v[214:215], v0 offset:34816
	ds_read_b64_tr_b16 v[216:217], v0 offset:35328
	ds_read_b64_tr_b16 v[220:221], v0 offset:27648
	ds_read_b64_tr_b16 v[222:223], v0 offset:28160
	v_cvt_pk_bf16_f32 v210, v199, v113
	v_cvt_pk_bf16_f32 v211, v201, v115
	v_cvt_pk_bf16_f32 v212, v203, v15
	v_cvt_pk_bf16_f32 v213, v13, v11
	v_exp_f32_e32 v209, v120
	v_exp_f32_e32 v207, v121
	s_waitcnt lgkmcnt(4)
	v_mfma_f32_32x32x16_bf16 v[16:31], v[96:99], v[210:213], v[16:31]
	v_exp_f32_e32 v205, v122
	v_exp_f32_e32 v121, v123
	v_exp_f32_e32 v117, v124
	ds_read_b64_tr_b16 v[224:225], v0 offset:35840
	ds_read_b64_tr_b16 v[226:227], v0 offset:36352
	v_exp_f32_e32 v119, v125
	v_exp_f32_e32 v99, v126
	v_exp_f32_e32 v97, v127
	s_waitcnt lgkmcnt(4)
	v_mfma_f32_32x32x16_bf16 v[32:47], v[214:217], v[210:213], v[32:47]
	v_cvt_pk_bf16_f32 v228, v209, v207
	v_cvt_pk_bf16_f32 v229, v205, v121
	v_cvt_pk_bf16_f32 v230, v117, v119
	v_cvt_pk_bf16_f32 v231, v99, v97
	v_exp_f32_e32 v125, v100
	v_exp_f32_e32 v213, v101
	v_exp_f32_e32 v211, v102
	s_waitcnt lgkmcnt(2)
	v_mfma_f32_32x32x16_bf16 v[16:31], v[220:223], v[228:231], v[16:31]
	v_exp_f32_e32 v217, v103
	ds_read_b64_tr_b16 v[220:221], v0 offset:28672
	ds_read_b64_tr_b16 v[222:223], v0 offset:29184
	v_cvt_pk_bf16_f32 v100, v7, v9
	v_cvt_pk_bf16_f32 v101, v3, v5
	v_cvt_pk_bf16_f32 v102, v125, v213
	v_cvt_pk_bf16_f32 v103, v211, v217
	v_exp_f32_e32 v123, v104
	s_waitcnt lgkmcnt(2)
	v_mfma_f32_32x32x16_bf16 v[32:47], v[224:227], v[228:231], v[32:47]
	ds_read_b64_tr_b16 v[224:225], v0 offset:36864
	ds_read_b64_tr_b16 v[226:227], v0 offset:37376
	ds_read_b64_tr_b16 v[228:229], v0 offset:29696
	ds_read_b64_tr_b16 v[230:231], v0 offset:30208
	v_exp_f32_e32 v127, v105
	v_exp_f32_e32 v105, v106
	v_exp_f32_e32 v215, v107
	v_exp_f32_e32 v107, v108
	v_exp_f32_e32 v109, v109
	v_exp_f32_e32 v198, v64
	s_waitcnt lgkmcnt(4)
	v_mfma_f32_32x32x16_bf16 v[16:31], v[220:223], v[100:103], v[16:31]
	ds_read_b64_tr_b16 v[220:221], v0 offset:37888
	ds_read_b64_tr_b16 v[222:223], v0 offset:38400
	v_exp_f32_e32 v6, v80
	v_exp_f32_e32 v112, v65
	v_exp_f32_e32 v8, v81
	v_exp_f32_e32 v200, v66
	v_exp_f32_e32 v2, v82
	v_exp_f32_e32 v114, v67
	s_waitcnt lgkmcnt(4)
	v_mfma_f32_32x32x16_bf16 v[32:47], v[224:227], v[100:103], v[32:47]
	v_exp_f32_e32 v103, v110
	v_exp_f32_e32 v101, v111
	v_exp_f32_e32 v4, v83
	v_cvt_pk_bf16_f32 v224, v123, v127
	v_cvt_pk_bf16_f32 v225, v105, v215
	v_cvt_pk_bf16_f32 v226, v107, v109
	v_cvt_pk_bf16_f32 v227, v103, v101
	v_pk_add_f32 v[64:65], v[6:7], v[198:199]
	v_pk_add_f32 v[66:67], v[8:9], v[112:113]
	s_waitcnt lgkmcnt(2)
	v_mfma_f32_32x32x16_bf16 v[16:31], v[228:231], v[224:227], v[16:31]
	v_add_f32_e64 v64, v64, 0
	v_add_f32_e64 v65, v65, 0
	v_exp_f32_e32 v202, v68
	v_pk_add_f32 v[64:65], v[66:67], v[64:65]
	v_pk_add_f32 v[66:67], v[2:3], v[200:201]
	v_exp_f32_e32 v14, v69
	v_pk_add_f32 v[64:65], v[66:67], v[64:65]
	v_pk_add_f32 v[66:67], v[4:5], v[114:115]
	s_waitcnt lgkmcnt(0)
	v_mfma_f32_32x32x16_bf16 v[32:47], v[220:223], v[224:227], v[32:47]
	v_add_f32_e64 v110, v66, v64
	v_add_f32_e64 v111, v67, v65
	v_exp_f32_e32 v12, v70
	v_exp_f32_e32 v10, v71
	ds_read_b64_tr_b16 v[64:65], v0 offset:30720
	ds_read_b64_tr_b16 v[66:67], v0 offset:31232
	v_exp_f32_e32 v124, v84
	v_exp_f32_e32 v208, v72
	v_exp_f32_e32 v206, v73
	v_exp_f32_e32 v204, v74
	v_exp_f32_e32 v120, v75
	ds_read_b64_tr_b16 v[72:73], v0 offset:38912
	ds_read_b64_tr_b16 v[74:75], v0 offset:39424
	ds_read_b64_tr_b16 v[80:81], v0 offset:31744
	ds_read_b64_tr_b16 v[82:83], v0 offset:32256
	v_exp_f32_e32 v212, v85
	v_cvt_pk_bf16_f32 v68, v198, v112
	v_cvt_pk_bf16_f32 v69, v200, v114
	v_cvt_pk_bf16_f32 v70, v202, v14
	v_cvt_pk_bf16_f32 v71, v12, v10
	v_pk_add_f32 v[220:221], v[124:125], v[202:203]
	v_exp_f32_e32 v210, v86
	s_waitcnt lgkmcnt(4)
; #define LAS __attribute__((address_space(3)))
; __device__ __forceinline__ void a2_pv(const LAS unsigned char* vb, const bf16x8 (&pf)[4], f32x16& ot0, f32x16& ot1) {
; #pragma unroll
;     for (int s = 0; s < 4; ++s) {
;         const s16x4 a00 = __builtin_bit_cast(s16x4, __builtin_amdgcn_ds_read_tr16_b64_v4i16((LAS s16x4*)(vb + (16 * s) * 64)));
;         const s16x4 a01 = __builtin_bit_cast(s16x4, __builtin_amdgcn_ds_read_tr16_b64_v4i16((LAS s16x4*)(vb + (16 * s + 8) * 64)));
;         const s16x4 a10 = __builtin_bit_cast(s16x4, __builtin_amdgcn_ds_read_tr16_b64_v4i16((LAS s16x4*)(vb + 8192 + (16 * s) * 64)));
;         const s16x4 a11 = __builtin_bit_cast(s16x4, __builtin_amdgcn_ds_read_tr16_b64_v4i16((LAS s16x4*)(vb + 8192 + (16 * s + 8) * 64)));
;         const bf16x8 va0 = (bf16x8){a00[0], a00[1], a00[2], a00[3], a01[0], a01[1], a01[2], a01[3]};
;         const bf16x8 va1 = (bf16x8){a10[0], a10[1], a10[2], a10[3], a11[0], a11[1], a11[2], a11[3]};
;         ot0 = __builtin_amdgcn_mfma_f32_32x32x16_bf16(va0, pf[s], ot0, 0, 0, 0); ot1 = __builtin_amdgcn_mfma_f32_32x32x16_bf16(va1, pf[s], ot1, 0, 0, 0); }
; }
; __device__ __forceinline__ void attn2_unit(bf16_t* Z, const bf16_t* Hb, const float* rc, const float* rs, LAS unsigned char* lds, int b, int h, int qblk) {
;     ...
;             a2_exp_pack(sa0, sa1, lsum, pa);
;             a2_pv(vb, pa, ot0, ot1);
;             a2_exp_pack(sb0, sb1, lsum, pb);
;             a2_pv(vb + 64 * 64, pb, ot0, ot1);
;         } else if (2 * kp <= cw) {
;             f32x16 sa0, sa1; bf16x8 pa[4];
;             a2_qk(kb, qf, cneg, sa0, sa1);
;             const float mt = a2_max(sa0, sa1);
;             if (kp == 0 || __builtin_amdgcn_ballot_w64(mt > 8.f) != 0ull) {
;                 const float delta = (kp == 0) ? mt : fmaxf(mt, 0.f), alpha = (kp == 0) ? 0.f : __builtin_amdgcn_exp2f(-delta);
;                 mrun += delta; lsum *= alpha;
; #pragma unroll
;                 for (int r = 0; r < 16; ++r) { ot0[r] *= alpha; ot1[r] *= alpha; sa0[r] -= delta; sa1[r] -= delta; cneg[r] = -mrun; }
;             }
;             a2_exp_pack(sa0, sa1, lsum, pa);
;             a2_pv(vb, pa, ot0, ot1);
;         }
;         __syncthreads();
;     }
	v_mfma_f32_32x32x16_bf16 v[16:31], v[64:67], v[68:71], v[16:31]
	v_add_f32_e64 v64, v220, v110
	v_add_f32_e64 v65, v221, v111
	v_add_f32_e64 v14, v212, v14
	v_add_f32_e64 v15, v213, v15
	v_exp_f32_e32 v216, v87
	v_exp_f32_e32 v116, v76
	v_exp_f32_e32 v118, v77
	v_exp_f32_e32 v98, v78
	v_exp_f32_e32 v96, v79
	s_waitcnt lgkmcnt(2)
	v_mfma_f32_32x32x16_bf16 v[32:47], v[72:75], v[68:71], v[32:47]
	v_add_f32_e64 v14, v14, v64
	v_add_f32_e64 v15, v15, v65
	ds_read_b64_tr_b16 v[64:65], v0 offset:39936
	ds_read_b64_tr_b16 v[66:67], v0 offset:40448
	v_exp_f32_e32 v122, v88
	v_pk_add_f32 v[12:13], v[210:211], v[12:13]
	v_pk_add_f32 v[68:69], v[216:217], v[10:11]
	v_pk_add_f32 v[14:15], v[12:13], v[14:15]
	v_cvt_pk_bf16_f32 v10, v208, v206
	v_cvt_pk_bf16_f32 v11, v204, v120
	v_cvt_pk_bf16_f32 v12, v116, v118
	v_cvt_pk_bf16_f32 v13, v98, v96
	v_pk_add_f32 v[14:15], v[68:69], v[14:15]
	v_pk_add_f32 v[68:69], v[122:123], v[208:209]
	s_waitcnt lgkmcnt(2)
	v_mfma_f32_32x32x16_bf16 v[16:31], v[80:83], v[10:13], v[16:31]
	v_add_f32_e64 v14, v68, v14
	v_add_f32_e64 v15, v69, v15
	ds_read_b64_tr_b16 v[68:69], v0 offset:32768
	ds_read_b64_tr_b16 v[70:71], v0 offset:33280
	v_exp_f32_e32 v126, v89
	v_exp_f32_e32 v104, v90
	v_cvt_pk_bf16_f32 v7, v2, v4
	v_exp_f32_e32 v214, v91
	v_cvt_pk_bf16_f32 v6, v6, v8
	s_waitcnt lgkmcnt(2)
	v_mfma_f32_32x32x16_bf16 v[32:47], v[64:67], v[10:13], v[32:47]
	ds_read_b64_tr_b16 v[2:3], v0 offset:40960
	ds_read_b64_tr_b16 v[4:5], v0 offset:41472
	ds_read_b64_tr_b16 v[10:11], v0 offset:33792
	ds_read_b64_tr_b16 v[12:13], v0 offset:34304
	v_cvt_pk_bf16_f32 v8, v124, v212
	v_cvt_pk_bf16_f32 v9, v210, v216
	v_pk_add_f32 v[72:73], v[126:127], v[206:207]
	v_pk_add_f32 v[64:65], v[104:105], v[204:205]
	v_pk_add_f32 v[14:15], v[72:73], v[14:15]
	v_exp_f32_e32 v106, v92
	s_waitcnt lgkmcnt(4)
	v_mfma_f32_32x32x16_bf16 v[16:31], v[68:71], v[6:9], v[16:31]
	v_add_f32_e64 v14, v64, v14
	v_add_f32_e64 v15, v65, v15
	v_add_f32_e64 v64, v214, v120
	v_add_f32_e64 v65, v215, v121
	v_exp_f32_e32 v108, v93
	v_exp_f32_e32 v102, v94
	v_exp_f32_e32 v100, v95
	v_pk_add_f32 v[14:15], v[64:65], v[14:15]
	ds_read_b64_tr_b16 v[64:65], v0 offset:41984
	ds_read_b64_tr_b16 v[66:67], v0 offset:42496
	s_waitcnt lgkmcnt(4)
	v_mfma_f32_32x32x16_bf16 v[32:47], v[2:5], v[6:9], v[32:47]
	v_add_f32_e64 v2, v106, v116
	v_add_f32_e64 v3, v107, v117
	v_cvt_pk_bf16_f32 v4, v106, v108
	v_add_f32_e64 v6, v2, v14
	v_add_f32_e64 v7, v3, v15
	v_cvt_pk_bf16_f32 v2, v122, v126
	v_cvt_pk_bf16_f32 v3, v104, v214
	v_cvt_pk_bf16_f32 v5, v102, v100
	v_pk_add_f32 v[8:9], v[108:109], v[118:119]
	s_waitcnt lgkmcnt(2)
	v_mfma_f32_32x32x16_bf16 v[16:31], v[10:13], v[2:5], v[16:31]
	v_add_f32_e64 v6, v8, v6
	v_add_f32_e64 v7, v9, v7
	v_add_f32_e64 v8, v102, v98
	v_add_f32_e64 v9, v103, v99
	v_pk_add_f32 v[6:7], v[8:9], v[6:7]
	v_pk_add_f32 v[8:9], v[100:101], v[96:97]
	v_pk_add_f32 v[6:7], v[8:9], v[6:7]
	s_waitcnt lgkmcnt(0)
	v_mfma_f32_32x32x16_bf16 v[32:47], v[64:67], v[2:5], v[32:47]
	v_add_f32_e32 v0, v169, v7
	v_add_f32_e32 v0, v6, v0
	s_add_i32 s47, s47, 1
	s_add_i32 s48, s48, 2
	s_add_i32 s6, s37, s47
	v_lshl_add_u64 v[176:177], v[176:177], 0, v[174:175]
	v_lshl_add_u64 v[178:179], v[178:179], 0, s[18:19]
	v_lshl_add_u64 v[180:181], v[180:181], 0, s[18:19]
	v_lshl_add_u64 v[184:185], v[184:185], 0, v[182:183]
	v_lshl_add_u64 v[188:189], v[188:189], 0, v[186:187]
	s_cmp_lg_u32 s6, 1
	v_lshl_add_u64 v[194:195], v[194:195], 0, v[190:191]
	s_cbranch_scc0 .Lattn_exit_2
	v_mov_b32_e32 v169, v0
	s_bitcmp1_b32 s47, 0
	s_cselect_b32 s6, 0, 0xa800
	s_cmp_ge_u32 s47, s34
	s_waitcnt vmcnt(0) lgkmcnt(0)
	s_barrier
	s_cbranch_scc0 .LBB0_2221
	s_branch .LBB0_2224

; #define LAS __attribute__((address_space(3)))
; __device__ __forceinline__ unsigned cvtpk2(float lo, float hi) { const f32x2 v = {lo, hi}; const bf16x2_n b = __builtin_convertvector(v, bf16x2_n); return __builtin_bit_cast(unsigned, b); }
; __device__ __forceinline__ void a2_exp_pack(f32x16& st0, f32x16& st1, float& lsum, bf16x8 (&pf)[4]) {
;     float ps = 0.f;
; #pragma unroll
;     for (int r = 0; r < 16; ++r) { st0[r] = __builtin_amdgcn_exp2f(st0[r]); st1[r] = __builtin_amdgcn_exp2f(st1[r]); ps += st0[r] + st1[r]; }
;     lsum += ps;
;     u32x4 w;
;     w.x = cvtpk2(st0[0], st0[1]); w.y = cvtpk2(st0[2], st0[3]); w.z = cvtpk2(st0[4], st0[5]); w.w = cvtpk2(st0[6], st0[7]); pf[0] = __builtin_bit_cast(bf16x8, w);
;     w.x = cvtpk2(st0[8], st0[9]); w.y = cvtpk2(st0[10], st0[11]); w.z = cvtpk2(st0[12], st0[13]); w.w = cvtpk2(st0[14], st0[15]); pf[1] = __builtin_bit_cast(bf16x8, w);
;     w.x = cvtpk2(st1[0], st1[1]); w.y = cvtpk2(st1[2], st1[3]); w.z = cvtpk2(st1[4], st1[5]); w.w = cvtpk2(st1[6], st1[7]); pf[2] = __builtin_bit_cast(bf16x8, w);
;     w.x = cvtpk2(st1[8], st1[9]); w.y = cvtpk2(st1[10], st1[11]); w.z = cvtpk2(st1[12], st1[13]); w.w = cvtpk2(st1[14], st1[15]); pf[3] = __builtin_bit_cast(bf16x8, w);
; }
; __device__ __forceinline__ void a2_pv(const LAS unsigned char* vb, const bf16x8 (&pf)[4], f32x16& ot0, f32x16& ot1) {
; #pragma unroll
;     for (int s = 0; s < 4; ++s) {
;         const s16x4 a00 = __builtin_bit_cast(s16x4, __builtin_amdgcn_ds_read_tr16_b64_v4i16((LAS s16x4*)(vb + (16 * s) * 64)));
;         const s16x4 a01 = __builtin_bit_cast(s16x4, __builtin_amdgcn_ds_read_tr16_b64_v4i16((LAS s16x4*)(vb + (16 * s + 8) * 64)));
;         const s16x4 a10 = __builtin_bit_cast(s16x4, __builtin_amdgcn_ds_read_tr16_b64_v4i16((LAS s16x4*)(vb + 8192 + (16 * s) * 64)));
;         const s16x4 a11 = __builtin_bit_cast(s16x4, __builtin_amdgcn_ds_read_tr16_b64_v4i16((LAS s16x4*)(vb + 8192 + (16 * s + 8) * 64)));
;         const bf16x8 va0 = (bf16x8){a00[0], a00[1], a00[2], a00[3], a01[0], a01[1], a01[2], a01[3]};
;         const bf16x8 va1 = (bf16x8){a10[0], a10[1], a10[2], a10[3], a11[0], a11[1], a11[2], a11[3]};
;         ot0 = __builtin_amdgcn_mfma_f32_32x32x16_bf16(va0, pf[s], ot0, 0, 0, 0); ot1 = __builtin_amdgcn_mfma_f32_32x32x16_bf16(va1, pf[s], ot1, 0, 0, 0); }
; }
.LBB0_2289:
	v_add_u32_e32 v0, v2, v218
	v_exp_f32_e32 v195, v112
	v_exp_f32_e32 v7, v96
	v_exp_f32_e32 v113, v113
	v_exp_f32_e32 v9, v97
	v_exp_f32_e32 v199, v114
	v_exp_f32_e32 v3, v98
	v_exp_f32_e32 v115, v115
	v_exp_f32_e32 v5, v99
	v_exp_f32_e32 v201, v116
	v_exp_f32_e32 v15, v117
	v_exp_f32_e32 v13, v118
	v_exp_f32_e32 v11, v119
	s_waitcnt vmcnt(0)
	ds_read_b64_tr_b16 v[96:97], v0 offset:26624
	ds_read_b64_tr_b16 v[98:99], v0 offset:27136
	ds_read_b64_tr_b16 v[212:213], v0 offset:34816
	ds_read_b64_tr_b16 v[214:215], v0 offset:35328
	ds_read_b64_tr_b16 v[220:221], v0 offset:27648
	ds_read_b64_tr_b16 v[222:223], v0 offset:28160
	v_cvt_pk_bf16_f32 v208, v195, v113
	v_cvt_pk_bf16_f32 v209, v199, v115
	v_cvt_pk_bf16_f32 v210, v201, v15
	v_cvt_pk_bf16_f32 v211, v13, v11
	v_exp_f32_e32 v207, v120
	v_exp_f32_e32 v205, v121
	s_waitcnt lgkmcnt(4)
	v_mfma_f32_32x32x16_bf16 v[16:31], v[96:99], v[208:211], v[16:31]
	v_exp_f32_e32 v203, v122
	v_exp_f32_e32 v121, v123
	v_exp_f32_e32 v117, v124
	ds_read_b64_tr_b16 v[224:225], v0 offset:35840
	ds_read_b64_tr_b16 v[226:227], v0 offset:36352
	v_exp_f32_e32 v119, v125
	v_exp_f32_e32 v99, v126
	v_exp_f32_e32 v97, v127
	s_waitcnt lgkmcnt(4)
	v_mfma_f32_32x32x16_bf16 v[32:47], v[212:215], v[208:211], v[32:47]
	v_cvt_pk_bf16_f32 v228, v207, v205
	v_cvt_pk_bf16_f32 v229, v203, v121
	v_cvt_pk_bf16_f32 v230, v117, v119
	v_cvt_pk_bf16_f32 v231, v99, v97
	v_exp_f32_e32 v125, v100
	v_exp_f32_e32 v211, v101
	v_exp_f32_e32 v209, v102
	s_waitcnt lgkmcnt(2)
	v_mfma_f32_32x32x16_bf16 v[16:31], v[220:223], v[228:231], v[16:31]
	v_exp_f32_e32 v215, v103
	ds_read_b64_tr_b16 v[220:221], v0 offset:28672
	ds_read_b64_tr_b16 v[222:223], v0 offset:29184
	v_cvt_pk_bf16_f32 v100, v7, v9
	v_cvt_pk_bf16_f32 v101, v3, v5
	v_cvt_pk_bf16_f32 v102, v125, v211
	v_cvt_pk_bf16_f32 v103, v209, v215
	v_exp_f32_e32 v123, v104
	s_waitcnt lgkmcnt(2)
	v_mfma_f32_32x32x16_bf16 v[32:47], v[224:227], v[228:231], v[32:47]
	ds_read_b64_tr_b16 v[224:225], v0 offset:36864
	ds_read_b64_tr_b16 v[226:227], v0 offset:37376
	ds_read_b64_tr_b16 v[228:229], v0 offset:29696
	ds_read_b64_tr_b16 v[230:231], v0 offset:30208
	v_exp_f32_e32 v127, v105
	v_exp_f32_e32 v105, v106
	v_exp_f32_e32 v213, v107
	v_exp_f32_e32 v107, v108
	v_exp_f32_e32 v109, v109
	v_exp_f32_e32 v194, v64
	s_waitcnt lgkmcnt(4)
	v_mfma_f32_32x32x16_bf16 v[16:31], v[220:223], v[100:103], v[16:31]
	ds_read_b64_tr_b16 v[220:221], v0 offset:37888
	ds_read_b64_tr_b16 v[222:223], v0 offset:38400
	v_exp_f32_e32 v6, v80
	v_exp_f32_e32 v112, v65
	v_exp_f32_e32 v8, v81
	v_exp_f32_e32 v198, v66
	v_exp_f32_e32 v2, v82
	v_exp_f32_e32 v114, v67
	s_waitcnt lgkmcnt(4)
	v_mfma_f32_32x32x16_bf16 v[32:47], v[224:227], v[100:103], v[32:47]
	v_exp_f32_e32 v103, v110
	v_exp_f32_e32 v101, v111
	v_exp_f32_e32 v4, v83
	v_cvt_pk_bf16_f32 v224, v123, v127
	v_cvt_pk_bf16_f32 v225, v105, v213
	v_cvt_pk_bf16_f32 v226, v107, v109
	v_cvt_pk_bf16_f32 v227, v103, v101
	v_pk_add_f32 v[64:65], v[6:7], v[194:195]
	v_pk_add_f32 v[66:67], v[8:9], v[112:113]
	s_waitcnt lgkmcnt(2)
	v_mfma_f32_32x32x16_bf16 v[16:31], v[228:231], v[224:227], v[16:31]
	v_add_f32_e64 v64, v64, 0
	v_add_f32_e64 v65, v65, 0
	v_exp_f32_e32 v200, v68
	v_pk_add_f32 v[64:65], v[66:67], v[64:65]
	v_pk_add_f32 v[66:67], v[2:3], v[198:199]
	v_exp_f32_e32 v14, v69
	v_pk_add_f32 v[64:65], v[66:67], v[64:65]
	v_pk_add_f32 v[66:67], v[4:5], v[114:115]
	s_waitcnt lgkmcnt(0)
	v_mfma_f32_32x32x16_bf16 v[32:47], v[220:223], v[224:227], v[32:47]
	v_add_f32_e64 v110, v66, v64
	v_add_f32_e64 v111, v67, v65
	v_exp_f32_e32 v12, v70
	v_exp_f32_e32 v10, v71
	ds_read_b64_tr_b16 v[64:65], v0 offset:30720
	ds_read_b64_tr_b16 v[66:67], v0 offset:31232
	v_exp_f32_e32 v124, v84
	v_exp_f32_e32 v206, v72
	v_exp_f32_e32 v204, v73
	v_exp_f32_e32 v202, v74
	v_exp_f32_e32 v120, v75
	ds_read_b64_tr_b16 v[72:73], v0 offset:38912
	ds_read_b64_tr_b16 v[74:75], v0 offset:39424
	ds_read_b64_tr_b16 v[80:81], v0 offset:31744
	ds_read_b64_tr_b16 v[82:83], v0 offset:32256
	v_exp_f32_e32 v210, v85
	v_cvt_pk_bf16_f32 v68, v194, v112
	v_cvt_pk_bf16_f32 v69, v198, v114
	v_cvt_pk_bf16_f32 v70, v200, v14
	v_cvt_pk_bf16_f32 v71, v12, v10
	v_pk_add_f32 v[216:217], v[124:125], v[200:201]
	v_exp_f32_e32 v208, v86
	s_waitcnt lgkmcnt(4)
	v_mfma_f32_32x32x16_bf16 v[16:31], v[64:67], v[68:71], v[16:31]
	v_add_f32_e64 v64, v216, v110
	v_add_f32_e64 v65, v217, v111
	v_add_f32_e64 v14, v210, v14
	v_add_f32_e64 v15, v211, v15
	v_exp_f32_e32 v214, v87
	v_exp_f32_e32 v116, v76
	v_exp_f32_e32 v118, v77
	v_exp_f32_e32 v98, v78
	v_exp_f32_e32 v96, v79
	s_waitcnt lgkmcnt(2)
; #define LAS __attribute__((address_space(3)))
; __device__ __forceinline__ void a2_pv(const LAS unsigned char* vb, const bf16x8 (&pf)[4], f32x16& ot0, f32x16& ot1) {
; #pragma unroll
;     for (int s = 0; s < 4; ++s) {
;         const s16x4 a00 = __builtin_bit_cast(s16x4, __builtin_amdgcn_ds_read_tr16_b64_v4i16((LAS s16x4*)(vb + (16 * s) * 64)));
;         const s16x4 a01 = __builtin_bit_cast(s16x4, __builtin_amdgcn_ds_read_tr16_b64_v4i16((LAS s16x4*)(vb + (16 * s + 8) * 64)));
;         const s16x4 a10 = __builtin_bit_cast(s16x4, __builtin_amdgcn_ds_read_tr16_b64_v4i16((LAS s16x4*)(vb + 8192 + (16 * s) * 64)));
;         const s16x4 a11 = __builtin_bit_cast(s16x4, __builtin_amdgcn_ds_read_tr16_b64_v4i16((LAS s16x4*)(vb + 8192 + (16 * s + 8) * 64)));
;         const bf16x8 va0 = (bf16x8){a00[0], a00[1], a00[2], a00[3], a01[0], a01[1], a01[2], a01[3]};
;         const bf16x8 va1 = (bf16x8){a10[0], a10[1], a10[2], a10[3], a11[0], a11[1], a11[2], a11[3]};
;         ot0 = __builtin_amdgcn_mfma_f32_32x32x16_bf16(va0, pf[s], ot0, 0, 0, 0); ot1 = __builtin_amdgcn_mfma_f32_32x32x16_bf16(va1, pf[s], ot1, 0, 0, 0); }
; }
; __device__ __forceinline__ void attn2_unit(bf16_t* Z, const bf16_t* Hb, const float* rc, const float* rs, LAS unsigned char* lds, int b, int h, int qblk) {
;     ...
;             a2_exp_pack(sa0, sa1, lsum, pa);
;             a2_pv(vb, pa, ot0, ot1);
;             a2_exp_pack(sb0, sb1, lsum, pb);
;             a2_pv(vb + 64 * 64, pb, ot0, ot1);
;         } else if (2 * kp <= cw) {
;             f32x16 sa0, sa1; bf16x8 pa[4];
;             a2_qk(kb, qf, cneg, sa0, sa1);
;             const float mt = a2_max(sa0, sa1);
;             if (kp == 0 || __builtin_amdgcn_ballot_w64(mt > 8.f) != 0ull) {
;                 const float delta = (kp == 0) ? mt : fmaxf(mt, 0.f), alpha = (kp == 0) ? 0.f : __builtin_amdgcn_exp2f(-delta);
;                 mrun += delta; lsum *= alpha;
; #pragma unroll
;                 for (int r = 0; r < 16; ++r) { ot0[r] *= alpha; ot1[r] *= alpha; sa0[r] -= delta; sa1[r] -= delta; cneg[r] = -mrun; }
;             }
;             a2_exp_pack(sa0, sa1, lsum, pa);
;             a2_pv(vb, pa, ot0, ot1);
;         }
;         __syncthreads();
;     }
	v_mfma_f32_32x32x16_bf16 v[32:47], v[72:75], v[68:71], v[32:47]
	v_add_f32_e64 v14, v14, v64
	v_add_f32_e64 v15, v15, v65
	ds_read_b64_tr_b16 v[64:65], v0 offset:39936
	ds_read_b64_tr_b16 v[66:67], v0 offset:40448
	v_exp_f32_e32 v122, v88
	v_pk_add_f32 v[12:13], v[208:209], v[12:13]
	v_pk_add_f32 v[68:69], v[214:215], v[10:11]
	v_pk_add_f32 v[14:15], v[12:13], v[14:15]
	v_cvt_pk_bf16_f32 v10, v206, v204
	v_cvt_pk_bf16_f32 v11, v202, v120
	v_cvt_pk_bf16_f32 v12, v116, v118
	v_cvt_pk_bf16_f32 v13, v98, v96
	v_pk_add_f32 v[14:15], v[68:69], v[14:15]
	v_pk_add_f32 v[68:69], v[122:123], v[206:207]
	s_waitcnt lgkmcnt(2)
	v_mfma_f32_32x32x16_bf16 v[16:31], v[80:83], v[10:13], v[16:31]
	v_add_f32_e64 v14, v68, v14
	v_add_f32_e64 v15, v69, v15
	ds_read_b64_tr_b16 v[68:69], v0 offset:32768
	ds_read_b64_tr_b16 v[70:71], v0 offset:33280
	v_exp_f32_e32 v126, v89
	v_exp_f32_e32 v104, v90
	v_cvt_pk_bf16_f32 v7, v2, v4
	v_exp_f32_e32 v212, v91
	v_cvt_pk_bf16_f32 v6, v6, v8
	s_waitcnt lgkmcnt(2)
	v_mfma_f32_32x32x16_bf16 v[32:47], v[64:67], v[10:13], v[32:47]
	ds_read_b64_tr_b16 v[2:3], v0 offset:40960
	ds_read_b64_tr_b16 v[4:5], v0 offset:41472
	ds_read_b64_tr_b16 v[10:11], v0 offset:33792
	ds_read_b64_tr_b16 v[12:13], v0 offset:34304
	v_cvt_pk_bf16_f32 v8, v124, v210
	v_cvt_pk_bf16_f32 v9, v208, v214
	v_pk_add_f32 v[72:73], v[126:127], v[204:205]
	v_pk_add_f32 v[64:65], v[104:105], v[202:203]
	v_pk_add_f32 v[14:15], v[72:73], v[14:15]
	v_exp_f32_e32 v106, v92
	s_waitcnt lgkmcnt(4)
	v_mfma_f32_32x32x16_bf16 v[16:31], v[68:71], v[6:9], v[16:31]
	v_add_f32_e64 v14, v64, v14
	v_add_f32_e64 v15, v65, v15
	v_add_f32_e64 v64, v212, v120
	v_add_f32_e64 v65, v213, v121
	v_exp_f32_e32 v108, v93
	v_exp_f32_e32 v102, v94
	v_exp_f32_e32 v100, v95
	v_pk_add_f32 v[14:15], v[64:65], v[14:15]
	ds_read_b64_tr_b16 v[64:65], v0 offset:41984
	ds_read_b64_tr_b16 v[66:67], v0 offset:42496
	s_waitcnt lgkmcnt(4)
	v_mfma_f32_32x32x16_bf16 v[32:47], v[2:5], v[6:9], v[32:47]
	v_add_f32_e64 v2, v106, v116
	v_add_f32_e64 v3, v107, v117
	v_cvt_pk_bf16_f32 v4, v106, v108
	v_add_f32_e64 v6, v2, v14
	v_add_f32_e64 v7, v3, v15
	v_cvt_pk_bf16_f32 v2, v122, v126
	v_cvt_pk_bf16_f32 v3, v104, v212
	v_cvt_pk_bf16_f32 v5, v102, v100
	v_pk_add_f32 v[8:9], v[108:109], v[118:119]
	s_waitcnt lgkmcnt(2)
	v_mfma_f32_32x32x16_bf16 v[16:31], v[10:13], v[2:5], v[16:31]
	v_add_f32_e64 v6, v8, v6
	v_add_f32_e64 v7, v9, v7
	v_add_f32_e64 v8, v102, v98
	v_add_f32_e64 v9, v103, v99
	v_pk_add_f32 v[6:7], v[8:9], v[6:7]
	v_pk_add_f32 v[8:9], v[100:101], v[96:97]
	v_pk_add_f32 v[6:7], v[8:9], v[6:7]
	s_waitcnt lgkmcnt(0)
	v_mfma_f32_32x32x16_bf16 v[32:47], v[64:67], v[2:5], v[32:47]
	v_add_f32_e32 v0, v169, v7
	v_add_f32_e32 v0, v6, v0
	s_add_i32 s31, s31, 1
	s_add_i32 s42, s42, 2
	s_add_i32 s6, s38, s31
	v_lshl_add_u64 v[174:175], v[174:175], 0, v[170:171]
	v_lshl_add_u64 v[176:177], v[176:177], 0, s[18:19]
	v_lshl_add_u64 v[178:179], v[178:179], 0, s[18:19]
	v_lshl_add_u64 v[182:183], v[182:183], 0, v[180:181]
	v_lshl_add_u64 v[186:187], v[186:187], 0, v[184:185]
	s_cmp_lg_u32 s6, 1
	v_lshl_add_u64 v[190:191], v[190:191], 0, v[188:189]
	s_cbranch_scc0 .Lattn_exit_3
	v_mov_b32_e32 v169, v0
	s_bitcmp1_b32 s31, 0
	s_cselect_b32 s6, 0, 0xa800
	s_cmp_ge_u32 s31, s36
	s_waitcnt vmcnt(0) lgkmcnt(0)
	s_barrier
	s_cbranch_scc0 .LBB0_2267
	s_branch .LBB0_2270
.Lattn_exit_3:
	s_waitcnt vmcnt(0) lgkmcnt(0)
	s_barrier
	s_nop 7
	s_nop 7
	v_mov_b32_e32 v14, v55
	v_mov_b32_e32 v10, v59
	v_mov_b32_e32 v11, v58
	v_mov_b64_e32 v[110:111], v[30:31]
	v_mov_b32_e32 v6, v63
	v_mov_b32_e32 v7, v62
	v_mov_b32_e32 v8, v61
	v_mov_b32_e32 v9, v60
	v_mov_b64_e32 v[126:127], v[46:47]
	v_mov_b32_e32 v12, v57
	v_mov_b32_e32 v13, v56
	v_mov_b32_e32 v15, v54
	v_mov_b32_e32 v194, v53
	v_mov_b32_e32 v195, v52
	v_mov_b32_e32 v198, v51
	v_mov_b32_e32 v199, v50
	v_mov_b32_e32 v200, v49
	v_mov_b32_e32 v4, v48
	v_mov_b32_e32 v5, v165
	v_mov_b64_e32 v[108:109], v[28:29]
	v_mov_b64_e32 v[106:107], v[26:27]
	v_mov_b64_e32 v[104:105], v[24:25]
	v_mov_b64_e32 v[102:103], v[22:23]
	v_mov_b64_e32 v[100:101], v[20:21]
	v_mov_b64_e32 v[98:99], v[18:19]
	v_mov_b64_e32 v[96:97], v[16:17]
	v_mov_b64_e32 v[124:125], v[44:45]
	v_mov_b64_e32 v[122:123], v[42:43]
	v_mov_b64_e32 v[120:121], v[40:41]
	v_mov_b64_e32 v[118:119], v[38:39]
	v_mov_b64_e32 v[116:117], v[36:37]
	v_mov_b64_e32 v[114:115], v[34:35]
	v_mov_b64_e32 v[112:113], v[32:33]
	s_branch .LBB0_2201
